# same as previous plus a 2-wait-state pad between the last residual-row store and the reduction that reuses its data registers
# baseline (speedup 1.0000x reference)
.LBB0_1036:
	s_lshl_b64 s[8:9], s[8:9], 2
	s_add_u32 s8, s16, s8
	s_addc_u32 s9, s17, s9
	s_add_u32 s10, s8, 0x2000
	s_addc_u32 s11, s9, 0
	global_load_dwordx4 v[110:113], v[132:133], off offset:16
	global_load_dwordx4 v[122:125], v[132:133], off
	global_load_dwordx4 v[106:109], v0, s[8:9] offset:16
	global_load_dwordx4 v[118:121], v0, s[8:9]
	global_load_dwordx4 v[114:117], v0, s[10:11] offset:16
	global_load_dwordx4 v[126:129], v0, s[10:11]
	global_load_dwordx4 v[86:89], v[132:133], off offset:2064
	global_load_dwordx4 v[98:101], v[132:133], off offset:2048
	global_load_dwordx4 v[82:85], v0, s[8:9] offset:2064
	global_load_dwordx4 v[94:97], v0, s[8:9] offset:2048
	global_load_dwordx4 v[90:93], v146, s[10:11] offset:16
	global_load_dwordx4 v[102:105], v146, s[10:11]
	global_load_dwordx4 v[62:65], v[134:135], off offset:16
	global_load_dwordx4 v[74:77], v[134:135], off
	global_load_dwordx4 v[58:61], v147, s[8:9] offset:16
	global_load_dwordx4 v[70:73], v147, s[8:9]
	global_load_dwordx4 v[66:69], v147, s[10:11] offset:16
	global_load_dwordx4 v[78:81], v147, s[10:11]
	global_load_dwordx4 v[38:41], v[136:137], off offset:16
	global_load_dwordx4 v[50:53], v[136:137], off
	global_load_dwordx4 v[34:37], v148, s[8:9] offset:16
	global_load_dwordx4 v[46:49], v148, s[8:9]
	global_load_dwordx4 v[42:45], v148, s[10:11] offset:16
	global_load_dwordx4 v[54:57], v148, s[10:11]
	s_and_b64 vcc, exec, s[4:5]
	s_cbranch_vccnz .LBB0_1029
	s_mov_b32 s3, s47
	s_lshl_b64 s[4:5], s[2:3], 12
	s_waitcnt vmcnt(0)
	v_cvt_pk_bf16_f32 v150, v30, v31
	v_cvt_pk_bf16_f32 v151, v32, v33
	v_cvt_pk_bf16_f32 v152, v26, v27
	v_cvt_pk_bf16_f32 v153, v28, v29
	v_lshl_add_u64 v[154:155], v[142:143], 0, s[4:5]
	global_store_dwordx4 v[154:155], v[150:153], off
	s_nop 1
	v_cvt_pk_bf16_f32 v150, v22, v23
	v_cvt_pk_bf16_f32 v151, v24, v25
	v_cvt_pk_bf16_f32 v152, v18, v19
	v_cvt_pk_bf16_f32 v153, v20, v21
	global_store_dwordx4 v[154:155], v[150:153], off offset:1024
	s_nop 1
	v_cvt_pk_bf16_f32 v150, v14, v15
	v_cvt_pk_bf16_f32 v151, v16, v17
	v_cvt_pk_bf16_f32 v152, v10, v11
	v_cvt_pk_bf16_f32 v153, v12, v13
	global_store_dwordx4 v[154:155], v[150:153], off offset:2048
	s_nop 1
	v_cvt_pk_bf16_f32 v150, v6, v7
	v_cvt_pk_bf16_f32 v151, v8, v9
	v_cvt_pk_bf16_f32 v152, v2, v3
	v_cvt_pk_bf16_f32 v153, v4, v5
	global_store_dwordx4 v[154:155], v[150:153], off offset:3072
	s_nop 1
	s_branch .LBB0_1029
